# tail backfill rebalanced: workgroups with a cheap last-round tile take fewer deferred transposes
# baseline (speedup 1.0000x reference)
; #define LAS __attribute__((address_space(3)))
; #define INP(i) ((const float*)(const GAS float*)KARG(8 * (i)))
; template <int KIND> __device__ __forceinline__ void tr_item(const float* __restrict__ W, int K, int Nsrc, const float* __restrict__ gk, bf16_t* WT, LAS float* scr, int item, int nblk, int lane) {
;     const int kb = item / nblk, nb = item - kb * nblk, k0 = 64 * kb, n0 = 32 * nb;
;     const int src = srcmap<KIND>(n0 + (lane & 31));
; #pragma unroll 8
;     for (int i = 0; i < 32; ++i) { const int kk = 2 * i + (lane >> 5); float v = 0.f; if (src >= 0) v = __builtin_nontemporal_load(&W[(size_t)(k0 + kk) * Nsrc + src]); if (gk) v *= gk[k0 + kk]; scr[kk * 33 + (lane & 31)] = v; }
; __global__ void __launch_bounds__(512, 2) fwd(Params P) {
;     ...
;         for (int it = gw; it < NITEMS; it += NGW) {
;             int r = it;
;             if (r < I0) { tr_item<1>(INP(4), 2048, 8256, nullptr, wb + OFF_WIN, scr, r, NIN / 32, lane); continue; } r -= I0;
;             if (r < I1) { tr_item<2>(INP(7), 512, 1536, INP(5), wb + OFF_WQ, scr, r, 1536 / 32, lane); continue; } r -= I1;
;             if (r < I2) { tr_item<0>(INP(8), 512, 2048, INP(6), wb + OFF_WKV, scr, r, 2048 / 32, lane); continue; } r -= I2;
;             if (r < I3) { tr_item<0>(INP(9), 1024, 2048, nullptr, wb + OFF_WSBO, scr, r, 2048 / 32, lane); continue; } r -= I3;
;             if (r < I4) { tr_item<0>(INP(10), 1024, 2048, nullptr, wb + OFF_WMLAO, scr, r, 2048 / 32, lane); continue; } r -= I4;
;             if (r < I5) { tr_item<0>(INP(11), 2048, 2048, nullptr, wb + OFF_WOUT, scr, r, 2048 / 32, lane); continue; } r -= I5;
;             if (r < I6) { tr_item<0>(INP(14), 2048, 8192, nullptr, wb + OFF_WUP, scr, r, 8192 / 32, lane); continue; } r -= I6;
;             if (r < I7) { tr_item<0>(INP(15), 8192, 2048, nullptr, wb + OFF_WDOWN, scr, r, 2048 / 32, lane); continue; } r -= I7;
;             if (r < I8) { tr_item<0>(INP(17), 256, 2048, nullptr, wb + OFF_WPLE, scr, r, 2048 / 32, lane); continue; } r -= I8;
;             tr_item<0>(INP(19), 2048, 2048, nullptr, wb + OFF_WPG, scr, r, 2048 / 32, lane);
.Lp1t_entry:
	v_readfirstlane_b32 s32, v178
	s_load_dwordx2 s[20:21], s[0:1], 0xa8
	v_lshrrev_b32_e32 v0, 5, v179
	v_and_b32_e32 v1, 31, v179
	v_lshrrev_b32_e32 v2, 3, v179
	v_and_b32_e32 v3, 7, v179
	s_lshr_b32 s32, s32, 6
	s_lshl_b32 s32, s32, 14
	v_lshlrev_b32_e32 v1, 2, v1
	v_mul_u32_u24_e32 v4, 0x84, v0
	v_mul_u32_u24_e32 v5, 0x420, v3
	v_add3_u32 v4, v4, v1, s32
	v_lshl_add_u32 v5, v2, 2, v5
	v_add_u32_e32 v5, s32, v5
	v_lshlrev_b32_e32 v3, 4, v3
	s_cmp_lt_u32 s84, 0x80
	s_mov_b32 s33, 0x7a7f
	s_cselect_b32 s33, 0x7d7f, s33
	s_mov_b32 s5, 0x5480
	s_cselect_b32 s5, 0x7a80, s5
	s_and_b32 s4, s84, 0x7f
	s_lshl_b32 s4, s4, 3
	s_add_i32 s4, s4, s5
	s_lshr_b32 s5, s32, 14
	s_add_i32 s4, s4, s5
	s_cmp_gt_i32 s4, s33
	s_cbranch_scc1 .Lp1t_skip
	s_waitcnt lgkmcnt(0)
	s_add_u32 s20, s20, 0x100000
	s_addc_u32 s21, s21, 0
	s_mov_b32 s16, 0x7580
	s_movk_i32 s15, 0x98
	s_mov_b32 s11, 13
	s_mov_b32 s12, 6
	s_mov_b32 s13, 11
	s_mov_b32 s14, 61603840
	s_cmpk_lt_u32 s4, 0x7580
	s_cselect_b32 s16, 0x7480, s16
	s_cselect_b32 s15, 0x88, s15
	s_cselect_b32 s11, 13, s11
	s_cselect_b32 s12, 6, s12
	s_cselect_b32 s13, 8, s13
	s_cselect_b32 s14, 61079552, s14
	s_cmpk_lt_u32 s4, 0x7480
	s_cselect_b32 s16, 0x5480, s16
	s_cselect_b32 s15, 0x78, s15
	s_cselect_b32 s11, 13, s11
	s_cselect_b32 s12, 6, s12
	s_cselect_b32 s13, 13, s13
	s_cselect_b32 s14, 44302336, s14
	s_cmpk_lt_u32 s4, 0x5480
	s_cselect_b32 s16, 0x3480, s16
	s_cselect_b32 s15, 0x70, s15
	s_cselect_b32 s11, 15, s11
	s_cselect_b32 s12, 8, s12
	s_cselect_b32 s13, 11, s13
	s_cselect_b32 s14, 27525120, s14
	s_cmpk_lt_u32 s4, 0x3480
	s_cselect_b32 s16, 0x2c80, s16
	s_cselect_b32 s15, 0x58, s15
	s_cselect_b32 s11, 13, s11
	s_cselect_b32 s12, 6, s12
	s_cselect_b32 s13, 11, s13
	s_cselect_b32 s14, 23330816, s14
	s_cmpk_lt_u32 s4, 0x2c80
	s_cselect_b32 s16, 0x2880, s16
	s_cselect_b32 s15, 0x50, s15
	s_cselect_b32 s11, 13, s11
	s_cselect_b32 s12, 6, s12
	s_cselect_b32 s13, 10, s13
	s_cselect_b32 s14, 21233664, s14
	s_cmpk_lt_u32 s4, 0x2880
	s_cselect_b32 s16, 0x2480, s16
	s_cselect_b32 s15, 0x48, s15
	s_cselect_b32 s11, 13, s11
	s_cselect_b32 s12, 6, s12
	s_cselect_b32 s13, 10, s13
	s_cselect_b32 s14, 19136512, s14
	s_load_dwordx2 s[6:7], s[0:1], s15
	s_sub_i32 s16, s4, s16
	s_lshl_b32 s19, 1, s12
	s_sub_i32 s19, s19, 1
	s_and_b32 s18, s16, s19
	s_lshr_b32 s17, s16, s12
	s_lshl_b32 s17, s17, 6
	s_lshl_b32 s19, s17, s11
	s_lshl_b32 s29, s18, 7
	s_add_u32 s19, s19, s29
	s_lshl_b32 s10, 2, s11
	v_lshlrev_b32_e32 v6, s11, v0
	v_add_u32_e32 v6, v6, v1
	s_lshl_b32 s29, s18, 5
	s_lshl_b32 s29, s29, s13
	s_add_u32 s29, s29, s17
	s_add_u32 s29, s29, s14
	s_lshl_b32 s29, s29, 1
	s_add_u32 s22, s20, s29
	s_addc_u32 s23, s21, 0
	s_lshl_b32 s24, 16, s13
	s_add_i32 s29, s13, 1
	v_lshlrev_b32_e32 v8, s29, v2
	v_add_u32_e32 v8, v8, v3
	s_waitcnt lgkmcnt(0)
	s_add_u32 s8, s6, s19
	s_addc_u32 s9, s7, 0
	global_load_dword v32, v6, s[8:9] nt
	s_add_u32 s8, s8, s10
	s_addc_u32 s9, s9, 0
	global_load_dword v33, v6, s[8:9] nt
	s_add_u32 s8, s8, s10
	s_addc_u32 s9, s9, 0
	global_load_dword v34, v6, s[8:9] nt
	s_add_u32 s8, s8, s10
	s_addc_u32 s9, s9, 0
	global_load_dword v35, v6, s[8:9] nt
	s_add_u32 s8, s8, s10
	s_addc_u32 s9, s9, 0
	global_load_dword v36, v6, s[8:9] nt
	s_add_u32 s8, s8, s10
	s_addc_u32 s9, s9, 0
	global_load_dword v37, v6, s[8:9] nt
	s_add_u32 s8, s8, s10
	s_addc_u32 s9, s9, 0
	global_load_dword v38, v6, s[8:9] nt
	s_add_u32 s8, s8, s10
	s_addc_u32 s9, s9, 0
	global_load_dword v39, v6, s[8:9] nt
	s_add_u32 s8, s8, s10
	s_addc_u32 s9, s9, 0
	global_load_dword v40, v6, s[8:9] nt
	s_add_u32 s8, s8, s10
	s_addc_u32 s9, s9, 0
	global_load_dword v41, v6, s[8:9] nt
	s_add_u32 s8, s8, s10
	s_addc_u32 s9, s9, 0
	global_load_dword v42, v6, s[8:9] nt
	s_add_u32 s8, s8, s10
	s_addc_u32 s9, s9, 0
	global_load_dword v43, v6, s[8:9] nt
	s_add_u32 s8, s8, s10
	s_addc_u32 s9, s9, 0
	global_load_dword v44, v6, s[8:9] nt
	s_add_u32 s8, s8, s10
	s_addc_u32 s9, s9, 0
	global_load_dword v45, v6, s[8:9] nt
	s_add_u32 s8, s8, s10
	s_addc_u32 s9, s9, 0
	global_load_dword v46, v6, s[8:9] nt
	s_add_u32 s8, s8, s10
	s_addc_u32 s9, s9, 0
	global_load_dword v47, v6, s[8:9] nt
	s_add_u32 s8, s8, s10
	s_addc_u32 s9, s9, 0
	global_load_dword v48, v6, s[8:9] nt
	s_add_u32 s8, s8, s10
	s_addc_u32 s9, s9, 0
	global_load_dword v49, v6, s[8:9] nt
	s_add_u32 s8, s8, s10
	s_addc_u32 s9, s9, 0
	global_load_dword v50, v6, s[8:9] nt
	s_add_u32 s8, s8, s10
	s_addc_u32 s9, s9, 0
	global_load_dword v51, v6, s[8:9] nt
	s_add_u32 s8, s8, s10
	s_addc_u32 s9, s9, 0
	global_load_dword v52, v6, s[8:9] nt
	s_add_u32 s8, s8, s10
	s_addc_u32 s9, s9, 0
	global_load_dword v53, v6, s[8:9] nt
	s_add_u32 s8, s8, s10
	s_addc_u32 s9, s9, 0
	global_load_dword v54, v6, s[8:9] nt
	s_add_u32 s8, s8, s10
	s_addc_u32 s9, s9, 0
	global_load_dword v55, v6, s[8:9] nt
	s_add_u32 s8, s8, s10
	s_addc_u32 s9, s9, 0
	global_load_dword v56, v6, s[8:9] nt
	s_add_u32 s8, s8, s10
	s_addc_u32 s9, s9, 0
	global_load_dword v57, v6, s[8:9] nt
	s_add_u32 s8, s8, s10
	s_addc_u32 s9, s9, 0
	global_load_dword v58, v6, s[8:9] nt
	s_add_u32 s8, s8, s10
	s_addc_u32 s9, s9, 0
	global_load_dword v59, v6, s[8:9] nt
	s_add_u32 s8, s8, s10
	s_addc_u32 s9, s9, 0
	global_load_dword v60, v6, s[8:9] nt
	s_add_u32 s8, s8, s10
	s_addc_u32 s9, s9, 0
	global_load_dword v61, v6, s[8:9] nt
	s_add_u32 s8, s8, s10
	s_addc_u32 s9, s9, 0
	global_load_dword v62, v6, s[8:9] nt
	s_add_u32 s8, s8, s10
	s_addc_u32 s9, s9, 0
	global_load_dword v63, v6, s[8:9] nt
	s_add_i32 s5, s4, 0x400
	s_cmp_gt_i32 s5, s33
	s_cbranch_scc1 .Lp1t_tail_a
; #define LAS __attribute__((address_space(3)))
; template <int KIND> __device__ __forceinline__ void tr_item(const float* __restrict__ W, int K, int Nsrc, const float* __restrict__ gk, bf16_t* WT, LAS float* scr, int item, int nblk, int lane) {
;     const int kb = item / nblk, nb = item - kb * nblk, k0 = 64 * kb, n0 = 32 * nb;
;     const int src = srcmap<KIND>(n0 + (lane & 31));
; #pragma unroll 8
;     for (int i = 0; i < 32; ++i) { const int kk = 2 * i + (lane >> 5); float v = 0.f; if (src >= 0) v = __builtin_nontemporal_load(&W[(size_t)(k0 + kk) * Nsrc + src]); if (gk) v *= gk[k0 + kk]; scr[kk * 33 + (lane & 31)] = v; }
	s_mov_b32 s16, 0x7580
	s_movk_i32 s15, 0x98
	s_mov_b32 s11, 13
	s_mov_b32 s12, 6
	s_mov_b32 s13, 11
	s_mov_b32 s14, 61603840
	s_cmpk_lt_u32 s5, 0x7580
	s_cselect_b32 s16, 0x7480, s16
	s_cselect_b32 s15, 0x88, s15
	s_cselect_b32 s11, 13, s11
	s_cselect_b32 s12, 6, s12
	s_cselect_b32 s13, 8, s13
	s_cselect_b32 s14, 61079552, s14
	s_cmpk_lt_u32 s5, 0x7480
	s_cselect_b32 s16, 0x5480, s16
	s_cselect_b32 s15, 0x78, s15
	s_cselect_b32 s11, 13, s11
	s_cselect_b32 s12, 6, s12
	s_cselect_b32 s13, 13, s13
	s_cselect_b32 s14, 44302336, s14
	s_cmpk_lt_u32 s5, 0x5480
	s_cselect_b32 s16, 0x3480, s16
	s_cselect_b32 s15, 0x70, s15
	s_cselect_b32 s11, 15, s11
	s_cselect_b32 s12, 8, s12
	s_cselect_b32 s13, 11, s13
	s_cselect_b32 s14, 27525120, s14
	s_cmpk_lt_u32 s5, 0x3480
	s_cselect_b32 s16, 0x2c80, s16
	s_cselect_b32 s15, 0x58, s15
	s_cselect_b32 s11, 13, s11
	s_cselect_b32 s12, 6, s12
	s_cselect_b32 s13, 11, s13
	s_cselect_b32 s14, 23330816, s14
	s_cmpk_lt_u32 s5, 0x2c80
	s_cselect_b32 s16, 0x2880, s16
	s_cselect_b32 s15, 0x50, s15
	s_cselect_b32 s11, 13, s11
	s_cselect_b32 s12, 6, s12
	s_cselect_b32 s13, 10, s13
	s_cselect_b32 s14, 21233664, s14
	s_cmpk_lt_u32 s5, 0x2880
	s_cselect_b32 s16, 0x2480, s16
	s_cselect_b32 s15, 0x48, s15
	s_cselect_b32 s11, 13, s11
	s_cselect_b32 s12, 6, s12
	s_cselect_b32 s13, 10, s13
	s_cselect_b32 s14, 19136512, s14
	s_load_dwordx2 s[6:7], s[0:1], s15
	s_sub_i32 s16, s5, s16
	s_lshl_b32 s19, 1, s12
	s_sub_i32 s19, s19, 1
	s_and_b32 s18, s16, s19
	s_lshr_b32 s17, s16, s12
	s_lshl_b32 s17, s17, 6
	s_lshl_b32 s19, s17, s11
	s_lshl_b32 s29, s18, 7
	s_add_u32 s19, s19, s29
	s_lshl_b32 s10, 2, s11
	v_lshlrev_b32_e32 v6, s11, v0
	v_add_u32_e32 v6, v6, v1
	s_lshl_b32 s29, s18, 5
	s_lshl_b32 s29, s29, s13
	s_add_u32 s29, s29, s17
	s_add_u32 s29, s29, s14
	s_lshl_b32 s29, s29, 1
	s_add_u32 s26, s20, s29
	s_addc_u32 s27, s21, 0
	s_lshl_b32 s28, 16, s13
	s_add_i32 s29, s13, 1
	v_lshlrev_b32_e32 v9, s29, v2
	v_add_u32_e32 v9, v9, v3
	s_waitcnt lgkmcnt(0)
	s_add_u32 s8, s6, s19
	s_addc_u32 s9, s7, 0
	global_load_dword v64, v6, s[8:9] nt
	s_add_u32 s8, s8, s10
	s_addc_u32 s9, s9, 0
	global_load_dword v65, v6, s[8:9] nt
	s_add_u32 s8, s8, s10
	s_addc_u32 s9, s9, 0
	global_load_dword v66, v6, s[8:9] nt
	s_add_u32 s8, s8, s10
	s_addc_u32 s9, s9, 0
	global_load_dword v67, v6, s[8:9] nt
	s_add_u32 s8, s8, s10
	s_addc_u32 s9, s9, 0
	global_load_dword v68, v6, s[8:9] nt
	s_add_u32 s8, s8, s10
	s_addc_u32 s9, s9, 0
	global_load_dword v69, v6, s[8:9] nt
	s_add_u32 s8, s8, s10
	s_addc_u32 s9, s9, 0
	global_load_dword v70, v6, s[8:9] nt
	s_add_u32 s8, s8, s10
	s_addc_u32 s9, s9, 0
	global_load_dword v71, v6, s[8:9] nt
	s_add_u32 s8, s8, s10
	s_addc_u32 s9, s9, 0
	global_load_dword v72, v6, s[8:9] nt
	s_add_u32 s8, s8, s10
	s_addc_u32 s9, s9, 0
	global_load_dword v73, v6, s[8:9] nt
	s_add_u32 s8, s8, s10
	s_addc_u32 s9, s9, 0
	global_load_dword v74, v6, s[8:9] nt
	s_add_u32 s8, s8, s10
	s_addc_u32 s9, s9, 0
	global_load_dword v75, v6, s[8:9] nt
	s_add_u32 s8, s8, s10
	s_addc_u32 s9, s9, 0
	global_load_dword v76, v6, s[8:9] nt
	s_add_u32 s8, s8, s10
	s_addc_u32 s9, s9, 0
	global_load_dword v77, v6, s[8:9] nt
	s_add_u32 s8, s8, s10
	s_addc_u32 s9, s9, 0
	global_load_dword v78, v6, s[8:9] nt
	s_add_u32 s8, s8, s10
	s_addc_u32 s9, s9, 0
	global_load_dword v79, v6, s[8:9] nt
	s_add_u32 s8, s8, s10
	s_addc_u32 s9, s9, 0
	global_load_dword v80, v6, s[8:9] nt
	s_add_u32 s8, s8, s10
	s_addc_u32 s9, s9, 0
	global_load_dword v81, v6, s[8:9] nt
	s_add_u32 s8, s8, s10
	s_addc_u32 s9, s9, 0
	global_load_dword v82, v6, s[8:9] nt
	s_add_u32 s8, s8, s10
	s_addc_u32 s9, s9, 0
	global_load_dword v83, v6, s[8:9] nt
	s_add_u32 s8, s8, s10
	s_addc_u32 s9, s9, 0
	global_load_dword v84, v6, s[8:9] nt
	s_add_u32 s8, s8, s10
	s_addc_u32 s9, s9, 0
	global_load_dword v85, v6, s[8:9] nt
	s_add_u32 s8, s8, s10
	s_addc_u32 s9, s9, 0
	global_load_dword v86, v6, s[8:9] nt
	s_add_u32 s8, s8, s10
	s_addc_u32 s9, s9, 0
	global_load_dword v87, v6, s[8:9] nt
	s_add_u32 s8, s8, s10
	s_addc_u32 s9, s9, 0
	global_load_dword v88, v6, s[8:9] nt
	s_add_u32 s8, s8, s10
	s_addc_u32 s9, s9, 0
	global_load_dword v89, v6, s[8:9] nt
	s_add_u32 s8, s8, s10
	s_addc_u32 s9, s9, 0
	global_load_dword v90, v6, s[8:9] nt
	s_add_u32 s8, s8, s10
	s_addc_u32 s9, s9, 0
	global_load_dword v91, v6, s[8:9] nt
	s_add_u32 s8, s8, s10
	s_addc_u32 s9, s9, 0
	global_load_dword v92, v6, s[8:9] nt
	s_add_u32 s8, s8, s10
	s_addc_u32 s9, s9, 0
	global_load_dword v93, v6, s[8:9] nt
	s_add_u32 s8, s8, s10
	s_addc_u32 s9, s9, 0
	global_load_dword v94, v6, s[8:9] nt
	s_add_u32 s8, s8, s10
	s_addc_u32 s9, s9, 0
	global_load_dword v95, v6, s[8:9] nt
	s_mov_b64 s[30:31], s[22:23]
	s_waitcnt vmcnt(63)
; #define LAS __attribute__((address_space(3)))
; __device__ __forceinline__ unsigned pk2(float lo, float hi) { return pg8::cvt_pk_bf16(lo, hi); }
; template <int KIND> __device__ __forceinline__ void tr_item(const float* __restrict__ W, int K, int Nsrc, const float* __restrict__ gk, bf16_t* WT, LAS float* scr, int item, int nblk, int lane) {
;     ...
;     for (int i = 0; i < 32; ++i) { const int kk = 2 * i + (lane >> 5); float v = 0.f; if (src >= 0) v = __builtin_nontemporal_load(&W[(size_t)(k0 + kk) * Nsrc + src]); if (gk) v *= gk[k0 + kk]; scr[kk * 33 + (lane & 31)] = v; }
;     asm volatile("s_waitcnt lgkmcnt(0)" ::: "memory");
;     const int c = lane & 7;
; #pragma unroll
;     for (int j = 0; j < 4; ++j) { const int n = (lane >> 3) + 8 * j; const LAS float* s = scr + (8 * c) * 33 + n;
;         u32x4 o; o.x = pk2(s[0 * 33], s[1 * 33]); o.y = pk2(s[2 * 33], s[3 * 33]); o.z = pk2(s[4 * 33], s[5 * 33]); o.w = pk2(s[6 * 33], s[7 * 33]);
;         *(u32x4*)(WT + (size_t)(n0 + n) * K + k0 + 8 * c) = o; }
	ds_write_b32 v4, v32
	s_waitcnt vmcnt(62)
	ds_write_b32 v4, v33 offset:264
	s_waitcnt vmcnt(61)
	ds_write_b32 v4, v34 offset:528
	s_waitcnt vmcnt(60)
	ds_write_b32 v4, v35 offset:792
	s_waitcnt vmcnt(59)
	ds_write_b32 v4, v36 offset:1056
	s_waitcnt vmcnt(58)
	ds_write_b32 v4, v37 offset:1320
	s_waitcnt vmcnt(57)
	ds_write_b32 v4, v38 offset:1584
	s_waitcnt vmcnt(56)
	ds_write_b32 v4, v39 offset:1848
	s_waitcnt vmcnt(55)
	ds_write_b32 v4, v40 offset:2112
	s_waitcnt vmcnt(54)
	ds_write_b32 v4, v41 offset:2376
	s_waitcnt vmcnt(53)
	ds_write_b32 v4, v42 offset:2640
	s_waitcnt vmcnt(52)
	ds_write_b32 v4, v43 offset:2904
	s_waitcnt vmcnt(51)
	ds_write_b32 v4, v44 offset:3168
	s_waitcnt vmcnt(50)
	ds_write_b32 v4, v45 offset:3432
	s_waitcnt vmcnt(49)
	ds_write_b32 v4, v46 offset:3696
	s_waitcnt vmcnt(48)
	ds_write_b32 v4, v47 offset:3960
	s_waitcnt vmcnt(47)
	ds_write_b32 v4, v48 offset:4224
	s_waitcnt vmcnt(46)
	ds_write_b32 v4, v49 offset:4488
	s_waitcnt vmcnt(45)
	ds_write_b32 v4, v50 offset:4752
	s_waitcnt vmcnt(44)
	ds_write_b32 v4, v51 offset:5016
	s_waitcnt vmcnt(43)
	ds_write_b32 v4, v52 offset:5280
	s_waitcnt vmcnt(42)
	ds_write_b32 v4, v53 offset:5544
	s_waitcnt vmcnt(41)
	ds_write_b32 v4, v54 offset:5808
	s_waitcnt vmcnt(40)
	ds_write_b32 v4, v55 offset:6072
	s_waitcnt vmcnt(39)
	ds_write_b32 v4, v56 offset:6336
	s_waitcnt vmcnt(38)
	ds_write_b32 v4, v57 offset:6600
	s_waitcnt vmcnt(37)
	ds_write_b32 v4, v58 offset:6864
	s_waitcnt vmcnt(36)
	ds_write_b32 v4, v59 offset:7128
	s_waitcnt vmcnt(35)
	ds_write_b32 v4, v60 offset:7392
	s_waitcnt vmcnt(34)
	ds_write_b32 v4, v61 offset:7656
	s_waitcnt vmcnt(33)
	ds_write_b32 v4, v62 offset:7920
	s_waitcnt vmcnt(32)
	ds_write_b32 v4, v63 offset:8184
	s_waitcnt lgkmcnt(0)
	ds_read2_b32 v[96:97], v5 offset0:0 offset1:8
	ds_read2_b32 v[98:99], v5 offset0:16 offset1:24
	ds_read2_b32 v[100:101], v5 offset0:33 offset1:41
	ds_read2_b32 v[102:103], v5 offset0:49 offset1:57
	ds_read2_b32 v[104:105], v5 offset0:66 offset1:74
	ds_read2_b32 v[106:107], v5 offset0:82 offset1:90
	ds_read2_b32 v[108:109], v5 offset0:99 offset1:107
	ds_read2_b32 v[110:111], v5 offset0:115 offset1:123
	ds_read2_b32 v[112:113], v5 offset0:132 offset1:140
	ds_read2_b32 v[114:115], v5 offset0:148 offset1:156
	ds_read2_b32 v[116:117], v5 offset0:165 offset1:173
	ds_read2_b32 v[118:119], v5 offset0:181 offset1:189
	ds_read2_b32 v[120:121], v5 offset0:198 offset1:206
	ds_read2_b32 v[122:123], v5 offset0:214 offset1:222
	ds_read2_b32 v[124:125], v5 offset0:231 offset1:239
	ds_read2_b32 v[126:127], v5 offset0:247 offset1:255
	s_waitcnt lgkmcnt(0)
	v_cvt_pk_bf16_f32 v12, v96, v100
	v_cvt_pk_bf16_f32 v13, v104, v108
	v_cvt_pk_bf16_f32 v14, v112, v116
	v_cvt_pk_bf16_f32 v15, v120, v124
	global_store_dwordx4 v8, v[12:15], s[30:31]
	s_add_u32 s30, s30, s24
	s_addc_u32 s31, s31, 0
	v_cvt_pk_bf16_f32 v16, v97, v101
	v_cvt_pk_bf16_f32 v17, v105, v109
	v_cvt_pk_bf16_f32 v18, v113, v117
	v_cvt_pk_bf16_f32 v19, v121, v125
	global_store_dwordx4 v8, v[16:19], s[30:31]
	s_add_u32 s30, s30, s24
	s_addc_u32 s31, s31, 0
	v_cvt_pk_bf16_f32 v12, v98, v102
	v_cvt_pk_bf16_f32 v13, v106, v110
	v_cvt_pk_bf16_f32 v14, v114, v118
	v_cvt_pk_bf16_f32 v15, v122, v126
	global_store_dwordx4 v8, v[12:15], s[30:31]
	s_add_u32 s30, s30, s24
	s_addc_u32 s31, s31, 0
	v_cvt_pk_bf16_f32 v16, v99, v103
	v_cvt_pk_bf16_f32 v17, v107, v111
	v_cvt_pk_bf16_f32 v18, v115, v119
	v_cvt_pk_bf16_f32 v19, v123, v127
	global_store_dwordx4 v8, v[16:19], s[30:31]
	s_mov_b32 s4, s5
